# in-proj epilogue: same cooperative 1/rms table as gate/up epilogue
# speedup vs baseline: 1.3368x; 1.0039x over previous
.LBB0_172:
	v_readlane_b32 s40, v253, 4
	v_readlane_b32 s41, v253, 5
	v_lshrrev_b32_e32 v133, 1, v146
	s_load_dwordx2 s[42:43], s[40:41], 0x98
	v_and_b32_e32 v132, 1, v146
	v_lshl_add_u32 v131, s46, 8, v133
	v_lshlrev_b32_e32 v131, 7, v131
	v_lshl_or_b32 v131, v132, 6, v131
	v_lshl_add_u32 v170, s46, 8, v149
	s_waitcnt lgkmcnt(0)
	s_add_u32 s40, s42, 0x1a700000
	s_addc_u32 s41, s43, 0
	global_load_dwordx4 v[236:239], v131, s[40:41]
	global_load_dwordx4 v[240:243], v131, s[40:41] offset:16
	global_load_dwordx4 v[244:247], v131, s[40:41] offset:32
	global_load_dwordx4 v[138:141], v131, s[40:41] offset:48
	s_mov_b32 s11, 0xf800000
	v_ashrrev_i32_e32 v171, 31, v170
	v_or_b32_e32 v176, 16, v170
	v_ashrrev_i32_e32 v177, 31, v176
	v_or_b32_e32 v180, 32, v170
	v_ashrrev_i32_e32 v181, 31, v180
	v_or_b32_e32 v184, 48, v170
	v_ashrrev_i32_e32 v185, 31, v184
	v_add_u32_e32 v188, 0x80, v170
	v_ashrrev_i32_e32 v189, 31, v188
	v_add_u32_e32 v192, 0x90, v170
	v_ashrrev_i32_e32 v193, 31, v192
	v_add_u32_e32 v196, 0xa0, v170
	v_ashrrev_i32_e32 v197, 31, v196
	v_add_u32_e32 v200, 0xb0, v170
	v_ashrrev_i32_e32 v201, 31, v200
	v_lshl_or_b32 v172, s37, 8, v179
	v_ashrrev_i32_e32 v173, 31, v172
	v_lshl_add_u64 v[154:155], v[172:173], 1, s[42:43]
	v_lshlrev_b32_e32 v133, 2, v133
	v_add_u32_e32 v133, 0x20240, v133
	s_waitcnt vmcnt(0)
	v_pk_add_f32 v[238:239], v[238:239], v[242:243]
	v_pk_add_f32 v[236:237], v[236:237], v[240:241]
	v_pk_add_f32 v[246:247], v[246:247], v[140:141]
	v_pk_add_f32 v[244:245], v[244:245], v[138:139]
	s_nop 0
	v_add_f32_e32 v236, v236, v237
	v_add_f32_e32 v238, v238, v239
	v_add_f32_e32 v244, v244, v245
	v_add_f32_e32 v246, v246, v247
	v_add_f32_e32 v236, v236, v238
	v_add_f32_e32 v244, v244, v246
	v_add_f32_e32 v236, v236, v244
	s_nop 1
	v_mov_b32_dpp v237, v236 quad_perm:[1,0,3,2] row_mask:0xf bank_mask:0xf
	s_nop 0
	v_add_f32_e32 v236, v236, v237
	v_fmamk_f32 v134, v236, 0x3a000000, v204
	v_cmp_gt_f32_e32 vcc, s11, v134
	v_mul_f32_e32 v135, 0x4f800000, v134
	s_nop 0
	v_cndmask_b32_e32 v134, v134, v135, vcc
	v_sqrt_f32_e32 v135, v134
	s_nop 0
	v_add_u32_e32 v136, -1, v135
	v_fma_f32 v137, -v136, v135, v134
	v_cmp_ge_f32_e64 s[40:41], 0, v137
	v_add_u32_e32 v137, 1, v135
	s_nop 0
	v_cndmask_b32_e64 v136, v135, v136, s[40:41]
	v_fma_f32 v135, -v137, v135, v134
	v_cmp_lt_f32_e64 s[40:41], 0, v135
	s_nop 1
	v_cndmask_b32_e64 v135, v136, v137, s[40:41]
	v_mul_f32_e32 v136, 0x37800000, v135
	v_cndmask_b32_e32 v135, v135, v136, vcc
	v_cmp_class_f32_e32 vcc, v134, v205
	s_nop 1
	v_cndmask_b32_e32 v134, v135, v134, vcc
	v_div_scale_f32 v135, s[40:41], v134, v134, 1.0
	v_rcp_f32_e32 v136, v135
	s_nop 0
	v_fma_f32 v137, -v135, v136, 1.0
	v_fmac_f32_e32 v136, v137, v136
	v_div_scale_f32 v137, vcc, 1.0, v134, 1.0
	v_mul_f32_e32 v142, v137, v136
	v_fma_f32 v143, -v135, v142, v137
	v_fmac_f32_e32 v142, v143, v136
	v_fma_f32 v135, -v135, v142, v137
	v_div_fmas_f32 v135, v135, v136, v142
	v_div_fixup_f32 v144, v135, v134, 1.0
	ds_write_b32 v133, v144
	v_lshlrev_b32_e32 v132, 2, v149
	v_add_u32_e32 v132, 0x20240, v132
	s_waitcnt lgkmcnt(0)
	s_barrier
	ds_read_b32 v174, v132
	ds_read_b32 v178, v132 offset:64
	ds_read_b32 v182, v132 offset:128
	ds_read_b32 v186, v132 offset:192
	ds_read_b32 v190, v132 offset:512
	ds_read_b32 v194, v132 offset:576
	ds_read_b32 v198, v132 offset:640
	ds_read_b32 v202, v132 offset:704
	s_mov_b32 s11, 0x5d20000
	s_mov_b64 s[40:41], 0x5d20000
	s_waitcnt lgkmcnt(0)
	v_lshl_add_u64 v[130:131], v[172:173], 2, s[42:43]
	v_lshl_add_u64 v[142:143], v[130:131], 0, s[40:41]
	v_add_co_u32_e32 v130, vcc, s11, v130
	s_mov_b64 s[40:41], 0x5f00000
	s_nop 0
	v_addc_co_u32_e32 v131, vcc, 0, v131, vcc
	global_load_dwordx4 v[134:137], v[130:131], off
	global_load_dwordx4 v[138:141], v[142:143], off offset:16
	s_nop 0
	global_load_dwordx4 v[130:133], v[142:143], off offset:528
	s_nop 0
	global_load_dwordx4 v[142:145], v[142:143], off offset:512
	v_lshl_add_u64 v[172:173], v[154:155], 0, s[40:41]
	v_lshlrev_b64 v[154:155], 13, v[170:171]
	v_lshl_add_u64 v[154:155], v[172:173], 0, v[154:155]
	s_mov_b64 s[40:41], -1
	s_andn2_b64 vcc, exec, s[38:39]
	s_waitcnt vmcnt(3)
	v_pk_fma_f32 v[128:129], v[128:129], v[174:175], v[136:137] op_sel_hi:[1,0,1]
	v_pk_fma_f32 v[126:127], v[126:127], v[174:175], v[134:135] op_sel_hi:[1,0,1]
	s_waitcnt vmcnt(2)
	v_pk_fma_f32 v[156:157], v[124:125], v[174:175], v[140:141] op_sel_hi:[1,0,1]
	v_pk_fma_f32 v[124:125], v[122:123], v[174:175], v[138:139] op_sel_hi:[1,0,1]
	v_cvt_pk_bf16_f32 v122, v126, v127
	v_cvt_pk_bf16_f32 v123, v128, v129
	v_cvt_pk_bf16_f32 v124, v124, v125
	v_cvt_pk_bf16_f32 v125, v156, v157
	global_store_dwordx4 v[154:155], v[122:125], off
	s_waitcnt vmcnt(1)
	v_pk_fma_f32 v[116:117], v[116:117], v[174:175], v[144:145] op_sel_hi:[1,0,1]
	v_pk_fma_f32 v[114:115], v[114:115], v[174:175], v[142:143] op_sel_hi:[1,0,1]
	v_pk_fma_f32 v[122:123], v[108:109], v[174:175], v[132:133] op_sel_hi:[1,0,1]
	v_pk_fma_f32 v[108:109], v[106:107], v[174:175], v[130:131] op_sel_hi:[1,0,1]
	v_cvt_pk_bf16_f32 v106, v114, v115
	v_cvt_pk_bf16_f32 v107, v116, v117
	v_cvt_pk_bf16_f32 v108, v108, v109
	v_cvt_pk_bf16_f32 v109, v122, v123
	global_store_dwordx4 v[154:155], v[106:109], off offset:256
	v_pk_fma_f32 v[112:113], v[112:113], v[178:179], v[140:141] op_sel_hi:[1,0,1]
	v_pk_fma_f32 v[110:111], v[110:111], v[178:179], v[138:139] op_sel_hi:[1,0,1]
	v_lshlrev_b64 v[106:107], 13, v[176:177]
	v_lshl_add_u64 v[114:115], v[172:173], 0, v[106:107]
	v_pk_fma_f32 v[108:109], v[120:121], v[178:179], v[136:137] op_sel_hi:[1,0,1]
	v_pk_fma_f32 v[106:107], v[118:119], v[178:179], v[134:135] op_sel_hi:[1,0,1]
	v_pk_fma_f32 v[100:101], v[100:101], v[178:179], v[144:145] op_sel_hi:[1,0,1]
	v_cvt_pk_bf16_f32 v106, v106, v107
	v_cvt_pk_bf16_f32 v107, v108, v109
	v_cvt_pk_bf16_f32 v108, v110, v111
	v_cvt_pk_bf16_f32 v109, v112, v113
	global_store_dwordx4 v[114:115], v[106:109], off
	v_pk_fma_f32 v[98:99], v[98:99], v[178:179], v[142:143] op_sel_hi:[1,0,1]
	v_pk_fma_f32 v[96:97], v[96:97], v[182:183], v[140:141] op_sel_hi:[1,0,1]
	v_pk_fma_f32 v[106:107], v[92:93], v[178:179], v[132:133] op_sel_hi:[1,0,1]
	v_pk_fma_f32 v[92:93], v[90:91], v[178:179], v[130:131] op_sel_hi:[1,0,1]
	v_cvt_pk_bf16_f32 v90, v98, v99
	v_cvt_pk_bf16_f32 v91, v100, v101
	v_cvt_pk_bf16_f32 v92, v92, v93
	v_cvt_pk_bf16_f32 v93, v106, v107
	global_store_dwordx4 v[114:115], v[90:93], off offset:256
	v_pk_fma_f32 v[94:95], v[94:95], v[182:183], v[138:139] op_sel_hi:[1,0,1]
	v_pk_fma_f32 v[84:85], v[84:85], v[182:183], v[144:145] op_sel_hi:[1,0,1]
	v_lshlrev_b64 v[90:91], 13, v[180:181]
	v_lshl_add_u64 v[98:99], v[172:173], 0, v[90:91]
	v_pk_fma_f32 v[92:93], v[104:105], v[182:183], v[136:137] op_sel_hi:[1,0,1]
	v_pk_fma_f32 v[90:91], v[102:103], v[182:183], v[134:135] op_sel_hi:[1,0,1]
	v_pk_fma_f32 v[82:83], v[82:83], v[182:183], v[142:143] op_sel_hi:[1,0,1]
	v_cvt_pk_bf16_f32 v90, v90, v91
	v_cvt_pk_bf16_f32 v91, v92, v93
	v_cvt_pk_bf16_f32 v92, v94, v95
	v_cvt_pk_bf16_f32 v93, v96, v97
	global_store_dwordx4 v[98:99], v[90:93], off
	v_pk_fma_f32 v[80:81], v[80:81], v[186:187], v[140:141] op_sel_hi:[1,0,1]
	v_pk_fma_f32 v[78:79], v[78:79], v[186:187], v[138:139] op_sel_hi:[1,0,1]
	v_pk_fma_f32 v[90:91], v[76:77], v[182:183], v[132:133] op_sel_hi:[1,0,1]
	v_pk_fma_f32 v[76:77], v[74:75], v[182:183], v[130:131] op_sel_hi:[1,0,1]
	v_cvt_pk_bf16_f32 v74, v82, v83
	v_cvt_pk_bf16_f32 v75, v84, v85
	v_cvt_pk_bf16_f32 v76, v76, v77
	v_cvt_pk_bf16_f32 v77, v90, v91
	global_store_dwordx4 v[98:99], v[74:77], off offset:256
	v_pk_fma_f32 v[72:73], v[72:73], v[186:187], v[144:145] op_sel_hi:[1,0,1]
	v_pk_fma_f32 v[70:71], v[70:71], v[186:187], v[142:143] op_sel_hi:[1,0,1]
	v_lshlrev_b64 v[74:75], 13, v[184:185]
	v_lshl_add_u64 v[82:83], v[172:173], 0, v[74:75]
	v_pk_fma_f32 v[76:77], v[88:89], v[186:187], v[136:137] op_sel_hi:[1,0,1]
	v_pk_fma_f32 v[74:75], v[86:87], v[186:187], v[134:135] op_sel_hi:[1,0,1]
	v_pk_fma_f32 v[64:65], v[64:65], v[190:191], v[136:137] op_sel_hi:[1,0,1]
	v_cvt_pk_bf16_f32 v74, v74, v75
	v_cvt_pk_bf16_f32 v75, v76, v77
	v_cvt_pk_bf16_f32 v76, v78, v79
	v_cvt_pk_bf16_f32 v77, v80, v81
	global_store_dwordx4 v[82:83], v[74:77], off
	v_pk_fma_f32 v[62:63], v[62:63], v[190:191], v[134:135] op_sel_hi:[1,0,1]
	v_pk_fma_f32 v[52:53], v[52:53], v[190:191], v[144:145] op_sel_hi:[1,0,1]
	v_pk_fma_f32 v[74:75], v[68:69], v[186:187], v[132:133] op_sel_hi:[1,0,1]
	v_pk_fma_f32 v[68:69], v[66:67], v[186:187], v[130:131] op_sel_hi:[1,0,1]
	v_cvt_pk_bf16_f32 v66, v70, v71
	v_cvt_pk_bf16_f32 v67, v72, v73
	v_cvt_pk_bf16_f32 v68, v68, v69
	v_cvt_pk_bf16_f32 v69, v74, v75
	global_store_dwordx4 v[82:83], v[66:69], off offset:256
	v_pk_fma_f32 v[50:51], v[50:51], v[190:191], v[142:143] op_sel_hi:[1,0,1]
	v_pk_fma_f32 v[48:49], v[48:49], v[194:195], v[140:141] op_sel_hi:[1,0,1]
	v_lshlrev_b64 v[66:67], 13, v[188:189]
	v_pk_fma_f32 v[68:69], v[60:61], v[190:191], v[140:141] op_sel_hi:[1,0,1]
	v_pk_fma_f32 v[60:61], v[58:59], v[190:191], v[138:139] op_sel_hi:[1,0,1]
	v_lshl_add_u64 v[66:67], v[172:173], 0, v[66:67]
	v_cvt_pk_bf16_f32 v58, v62, v63
	v_cvt_pk_bf16_f32 v59, v64, v65
	v_cvt_pk_bf16_f32 v60, v60, v61
	v_cvt_pk_bf16_f32 v61, v68, v69
	global_store_dwordx4 v[66:67], v[58:61], off
	v_pk_fma_f32 v[46:47], v[46:47], v[194:195], v[138:139] op_sel_hi:[1,0,1]
	v_pk_fma_f32 v[36:37], v[36:37], v[194:195], v[144:145] op_sel_hi:[1,0,1]
	v_pk_fma_f32 v[58:59], v[44:45], v[190:191], v[132:133] op_sel_hi:[1,0,1]
	v_pk_fma_f32 v[44:45], v[42:43], v[190:191], v[130:131] op_sel_hi:[1,0,1]
	v_cvt_pk_bf16_f32 v42, v50, v51
	v_cvt_pk_bf16_f32 v43, v52, v53
	v_cvt_pk_bf16_f32 v44, v44, v45
	v_cvt_pk_bf16_f32 v45, v58, v59
	global_store_dwordx4 v[66:67], v[42:45], off offset:256
	v_pk_fma_f32 v[34:35], v[34:35], v[194:195], v[142:143] op_sel_hi:[1,0,1]
	v_pk_fma_f32 v[32:33], v[32:33], v[198:199], v[140:141] op_sel_hi:[1,0,1]
	v_lshlrev_b64 v[42:43], 13, v[192:193]
	v_lshl_add_u64 v[50:51], v[172:173], 0, v[42:43]
	v_pk_fma_f32 v[44:45], v[56:57], v[194:195], v[136:137] op_sel_hi:[1,0,1]
	v_pk_fma_f32 v[42:43], v[54:55], v[194:195], v[134:135] op_sel_hi:[1,0,1]
	v_pk_fma_f32 v[30:31], v[30:31], v[198:199], v[138:139] op_sel_hi:[1,0,1]
	v_cvt_pk_bf16_f32 v42, v42, v43
	v_cvt_pk_bf16_f32 v43, v44, v45
	v_cvt_pk_bf16_f32 v44, v46, v47
	v_cvt_pk_bf16_f32 v45, v48, v49
	global_store_dwordx4 v[50:51], v[42:45], off
	v_pk_fma_f32 v[20:21], v[20:21], v[198:199], v[144:145] op_sel_hi:[1,0,1]
	v_pk_fma_f32 v[18:19], v[18:19], v[198:199], v[142:143] op_sel_hi:[1,0,1]
	v_pk_fma_f32 v[42:43], v[28:29], v[194:195], v[132:133] op_sel_hi:[1,0,1]
	v_pk_fma_f32 v[28:29], v[26:27], v[194:195], v[130:131] op_sel_hi:[1,0,1]
	v_cvt_pk_bf16_f32 v26, v34, v35
	v_cvt_pk_bf16_f32 v27, v36, v37
	v_cvt_pk_bf16_f32 v28, v28, v29
	v_cvt_pk_bf16_f32 v29, v42, v43
	global_store_dwordx4 v[50:51], v[26:29], off offset:256
	v_pk_fma_f32 v[16:17], v[16:17], v[202:203], v[140:141] op_sel_hi:[1,0,1]
	v_pk_fma_f32 v[14:15], v[14:15], v[202:203], v[138:139] op_sel_hi:[1,0,1]
	v_lshlrev_b64 v[26:27], 13, v[196:197]
	v_lshl_add_u64 v[34:35], v[172:173], 0, v[26:27]
	v_pk_fma_f32 v[28:29], v[40:41], v[198:199], v[136:137] op_sel_hi:[1,0,1]
	v_pk_fma_f32 v[26:27], v[38:39], v[198:199], v[134:135] op_sel_hi:[1,0,1]
	v_pk_fma_f32 v[8:9], v[8:9], v[202:203], v[144:145] op_sel_hi:[1,0,1]
	v_cvt_pk_bf16_f32 v26, v26, v27
	v_cvt_pk_bf16_f32 v27, v28, v29
	v_cvt_pk_bf16_f32 v28, v30, v31
	v_cvt_pk_bf16_f32 v29, v32, v33
	global_store_dwordx4 v[34:35], v[26:29], off
	v_pk_fma_f32 v[6:7], v[6:7], v[202:203], v[142:143] op_sel_hi:[1,0,1]
	s_nop 0
	v_pk_fma_f32 v[26:27], v[12:13], v[198:199], v[132:133] op_sel_hi:[1,0,1]
	v_pk_fma_f32 v[12:13], v[10:11], v[198:199], v[130:131] op_sel_hi:[1,0,1]
	v_cvt_pk_bf16_f32 v10, v18, v19
	v_cvt_pk_bf16_f32 v11, v20, v21
	v_cvt_pk_bf16_f32 v12, v12, v13
	v_cvt_pk_bf16_f32 v13, v26, v27
	global_store_dwordx4 v[34:35], v[10:13], off offset:256
	s_nop 1
	v_lshlrev_b64 v[10:11], 13, v[200:201]
	v_lshl_add_u64 v[18:19], v[172:173], 0, v[10:11]
	v_pk_fma_f32 v[12:13], v[24:25], v[202:203], v[136:137] op_sel_hi:[1,0,1]
	v_pk_fma_f32 v[10:11], v[22:23], v[202:203], v[134:135] op_sel_hi:[1,0,1]
	s_nop 0
	v_cvt_pk_bf16_f32 v10, v10, v11
	v_cvt_pk_bf16_f32 v11, v12, v13
	v_cvt_pk_bf16_f32 v12, v14, v15
	v_cvt_pk_bf16_f32 v13, v16, v17
	global_store_dwordx4 v[18:19], v[10:13], off
	s_nop 1
	v_pk_fma_f32 v[10:11], v[4:5], v[202:203], v[132:133] op_sel_hi:[1,0,1]
	v_pk_fma_f32 v[4:5], v[2:3], v[202:203], v[130:131] op_sel_hi:[1,0,1]
	v_cvt_pk_bf16_f32 v2, v6, v7
	v_cvt_pk_bf16_f32 v3, v8, v9
	v_cvt_pk_bf16_f32 v4, v4, v5
	v_cvt_pk_bf16_f32 v5, v10, v11
	global_store_dwordx4 v[18:19], v[2:5], off offset:256
	s_cbranch_vccnz .LBB0_161
	s_andn2_b64 vcc, exec, s[6:7]
	s_cbranch_vccnz .LBB0_160
	s_barrier
	s_branch .LBB0_160
